# hand-written residual GEMM epilogue: loads pipelined up front, v_pk_fma for x+alpha*acc, v_dot2c for row sum of squares, permlane swaps instead of ds_bpermute
# speedup vs baseline: 1.0045x; 1.0030x over previous
.LBB0_313:
	v_lshl_add_u32 v156, s20, 8, v160
	v_lshl_or_b32 v157, s1, 8, v162
	s_lshl_b32 s84, s1, 2
	s_add_i32 s84, s84, s57
	s_lshl_b32 s84, s84, 2
	v_lshlrev_b32_e32 v158, 11, v156
	v_lshl_add_u32 v158, v157, 1, v158
	v_lshl_add_u32 v159, v156, 6, s84
	v_mov_b64_e32 v[188:189], 0
	v_mov_b64_e32 v[190:191], 0
	v_mov_b64_e32 v[192:193], 0
	v_mov_b64_e32 v[252:253], 0
	v_mov_b32_e32 v180, v158
	global_load_dwordx4 v[220:223], v180, s[12:13]
	global_load_dwordx4 v[224:227], v180, s[12:13] offset:256
	v_add_u32_e32 v180, 0x8000, v158
	global_load_dwordx4 v[228:231], v180, s[12:13]
	global_load_dwordx4 v[232:235], v180, s[12:13] offset:256
	v_add_u32_e32 v180, 0x10000, v158
	global_load_dwordx4 v[236:239], v180, s[12:13]
	global_load_dwordx4 v[240:243], v180, s[12:13] offset:256
	v_add_u32_e32 v180, 0x18000, v158
	global_load_dwordx4 v[244:247], v180, s[12:13]
	global_load_dwordx4 v[248:251], v180, s[12:13] offset:256
	v_add_u32_e32 v180, 0x40000, v158
	global_load_dwordx4 v[164:167], v180, s[12:13]
	global_load_dwordx4 v[168:171], v180, s[12:13] offset:256
	v_add_u32_e32 v180, 0x48000, v158
	global_load_dwordx4 v[172:175], v180, s[12:13]
	global_load_dwordx4 v[176:179], v180, s[12:13] offset:256
	s_waitcnt vmcnt(10)
	v_lshlrev_b32_e32 v148, 16, v220
	v_and_b32_e32 v149, 0xffff0000, v220
	v_lshlrev_b32_e32 v150, 16, v221
	v_and_b32_e32 v151, 0xffff0000, v221
	v_lshlrev_b32_e32 v152, 16, v222
	v_and_b32_e32 v153, 0xffff0000, v222
	v_lshlrev_b32_e32 v154, 16, v223
	v_and_b32_e32 v155, 0xffff0000, v223
	v_pk_fma_f32 v[128:129], v[128:129], s[70:71], v[148:149]
	v_pk_fma_f32 v[130:131], v[130:131], s[70:71], v[150:151]
	v_pk_fma_f32 v[124:125], v[124:125], s[70:71], v[152:153]
	v_pk_fma_f32 v[126:127], v[126:127], s[70:71], v[154:155]
	v_cvt_pk_bf16_f32 v220, v128, v129
	v_cvt_pk_bf16_f32 v221, v130, v131
	v_cvt_pk_bf16_f32 v222, v124, v125
	v_cvt_pk_bf16_f32 v223, v126, v127
	v_dot2c_f32_bf16_e32 v188, v220, v220
	v_dot2c_f32_bf16_e32 v188, v221, v221
	v_dot2c_f32_bf16_e32 v188, v222, v222
	v_dot2c_f32_bf16_e32 v188, v223, v223
	v_lshlrev_b32_e32 v148, 16, v224
	v_and_b32_e32 v149, 0xffff0000, v224
	v_lshlrev_b32_e32 v150, 16, v225
	v_and_b32_e32 v151, 0xffff0000, v225
	v_lshlrev_b32_e32 v152, 16, v226
	v_and_b32_e32 v153, 0xffff0000, v226
	v_lshlrev_b32_e32 v154, 16, v227
	v_and_b32_e32 v155, 0xffff0000, v227
	v_pk_fma_f32 v[120:121], v[120:121], s[70:71], v[148:149]
	v_pk_fma_f32 v[122:123], v[122:123], s[70:71], v[150:151]
	v_pk_fma_f32 v[116:117], v[116:117], s[70:71], v[152:153]
	v_pk_fma_f32 v[118:119], v[118:119], s[70:71], v[154:155]
	v_cvt_pk_bf16_f32 v224, v120, v121
	v_cvt_pk_bf16_f32 v225, v122, v123
	v_cvt_pk_bf16_f32 v226, v116, v117
	v_cvt_pk_bf16_f32 v227, v118, v119
	v_dot2c_f32_bf16_e32 v188, v224, v224
	v_dot2c_f32_bf16_e32 v188, v225, v225
	v_dot2c_f32_bf16_e32 v188, v226, v226
	v_dot2c_f32_bf16_e32 v188, v227, v227
	v_mov_b32_e32 v180, v158
	global_store_dwordx4 v180, v[220:223], s[12:13]
	global_store_dwordx4 v180, v[224:227], s[12:13] offset:256
	s_nop 1
	v_add_u32_e32 v180, 0x50000, v158
	global_load_dwordx4 v[220:223], v180, s[12:13]
	global_load_dwordx4 v[224:227], v180, s[12:13] offset:256
	s_waitcnt vmcnt(12)
	v_lshlrev_b32_e32 v148, 16, v228
	v_and_b32_e32 v149, 0xffff0000, v228
	v_lshlrev_b32_e32 v150, 16, v229
	v_and_b32_e32 v151, 0xffff0000, v229
	v_lshlrev_b32_e32 v152, 16, v230
	v_and_b32_e32 v153, 0xffff0000, v230
	v_lshlrev_b32_e32 v154, 16, v231
	v_and_b32_e32 v155, 0xffff0000, v231
	v_pk_fma_f32 v[112:113], v[112:113], s[70:71], v[148:149]
	v_pk_fma_f32 v[114:115], v[114:115], s[70:71], v[150:151]
	v_pk_fma_f32 v[108:109], v[108:109], s[70:71], v[152:153]
	v_pk_fma_f32 v[110:111], v[110:111], s[70:71], v[154:155]
	v_cvt_pk_bf16_f32 v228, v112, v113
	v_cvt_pk_bf16_f32 v229, v114, v115
	v_cvt_pk_bf16_f32 v230, v108, v109
	v_cvt_pk_bf16_f32 v231, v110, v111
	v_dot2c_f32_bf16_e32 v189, v228, v228
	v_dot2c_f32_bf16_e32 v189, v229, v229
	v_dot2c_f32_bf16_e32 v189, v230, v230
	v_dot2c_f32_bf16_e32 v189, v231, v231
	v_lshlrev_b32_e32 v148, 16, v232
	v_and_b32_e32 v149, 0xffff0000, v232
	v_lshlrev_b32_e32 v150, 16, v233
	v_and_b32_e32 v151, 0xffff0000, v233
	v_lshlrev_b32_e32 v152, 16, v234
	v_and_b32_e32 v153, 0xffff0000, v234
	v_lshlrev_b32_e32 v154, 16, v235
	v_and_b32_e32 v155, 0xffff0000, v235
	v_pk_fma_f32 v[104:105], v[104:105], s[70:71], v[148:149]
	v_pk_fma_f32 v[106:107], v[106:107], s[70:71], v[150:151]
	v_pk_fma_f32 v[100:101], v[100:101], s[70:71], v[152:153]
	v_pk_fma_f32 v[102:103], v[102:103], s[70:71], v[154:155]
	v_cvt_pk_bf16_f32 v232, v104, v105
	v_cvt_pk_bf16_f32 v233, v106, v107
	v_cvt_pk_bf16_f32 v234, v100, v101
	v_cvt_pk_bf16_f32 v235, v102, v103
	v_dot2c_f32_bf16_e32 v189, v232, v232
	v_dot2c_f32_bf16_e32 v189, v233, v233
	v_dot2c_f32_bf16_e32 v189, v234, v234
	v_dot2c_f32_bf16_e32 v189, v235, v235
	v_add_u32_e32 v180, 0x8000, v158
	global_store_dwordx4 v180, v[228:231], s[12:13]
	global_store_dwordx4 v180, v[232:235], s[12:13] offset:256
	s_nop 1
	v_add_u32_e32 v180, 0x58000, v158
	global_load_dwordx4 v[228:231], v180, s[12:13]
	global_load_dwordx4 v[232:235], v180, s[12:13] offset:256
	s_waitcnt vmcnt(14)
	v_lshlrev_b32_e32 v148, 16, v236
	v_and_b32_e32 v149, 0xffff0000, v236
	v_lshlrev_b32_e32 v150, 16, v237
	v_and_b32_e32 v151, 0xffff0000, v237
	v_lshlrev_b32_e32 v152, 16, v238
	v_and_b32_e32 v153, 0xffff0000, v238
	v_lshlrev_b32_e32 v154, 16, v239
	v_and_b32_e32 v155, 0xffff0000, v239
	v_pk_fma_f32 v[92:93], v[92:93], s[70:71], v[148:149]
	v_pk_fma_f32 v[94:95], v[94:95], s[70:71], v[150:151]
	v_pk_fma_f32 v[88:89], v[88:89], s[70:71], v[152:153]
	v_pk_fma_f32 v[90:91], v[90:91], s[70:71], v[154:155]
	v_cvt_pk_bf16_f32 v236, v92, v93
	v_cvt_pk_bf16_f32 v237, v94, v95
	v_cvt_pk_bf16_f32 v238, v88, v89
	v_cvt_pk_bf16_f32 v239, v90, v91
	v_dot2c_f32_bf16_e32 v190, v236, v236
	v_dot2c_f32_bf16_e32 v190, v237, v237
	v_dot2c_f32_bf16_e32 v190, v238, v238
	v_dot2c_f32_bf16_e32 v190, v239, v239
	v_lshlrev_b32_e32 v148, 16, v240
	v_and_b32_e32 v149, 0xffff0000, v240
	v_lshlrev_b32_e32 v150, 16, v241
	v_and_b32_e32 v151, 0xffff0000, v241
	v_lshlrev_b32_e32 v152, 16, v242
	v_and_b32_e32 v153, 0xffff0000, v242
	v_lshlrev_b32_e32 v154, 16, v243
	v_and_b32_e32 v155, 0xffff0000, v243
	v_pk_fma_f32 v[84:85], v[84:85], s[70:71], v[148:149]
	v_pk_fma_f32 v[86:87], v[86:87], s[70:71], v[150:151]
	v_pk_fma_f32 v[80:81], v[80:81], s[70:71], v[152:153]
	v_pk_fma_f32 v[82:83], v[82:83], s[70:71], v[154:155]
	v_cvt_pk_bf16_f32 v240, v84, v85
	v_cvt_pk_bf16_f32 v241, v86, v87
	v_cvt_pk_bf16_f32 v242, v80, v81
	v_cvt_pk_bf16_f32 v243, v82, v83
	v_dot2c_f32_bf16_e32 v190, v240, v240
	v_dot2c_f32_bf16_e32 v190, v241, v241
	v_dot2c_f32_bf16_e32 v190, v242, v242
	v_dot2c_f32_bf16_e32 v190, v243, v243
	v_add_u32_e32 v180, 0x10000, v158
	global_store_dwordx4 v180, v[236:239], s[12:13]
	global_store_dwordx4 v180, v[240:243], s[12:13] offset:256
	s_waitcnt vmcnt(14)
	v_lshlrev_b32_e32 v148, 16, v244
	v_and_b32_e32 v149, 0xffff0000, v244
	v_lshlrev_b32_e32 v150, 16, v245
	v_and_b32_e32 v151, 0xffff0000, v245
	v_lshlrev_b32_e32 v152, 16, v246
	v_and_b32_e32 v153, 0xffff0000, v246
	v_lshlrev_b32_e32 v154, 16, v247
	v_and_b32_e32 v155, 0xffff0000, v247
	v_pk_fma_f32 v[76:77], v[76:77], s[70:71], v[148:149]
	v_pk_fma_f32 v[78:79], v[78:79], s[70:71], v[150:151]
	v_pk_fma_f32 v[72:73], v[72:73], s[70:71], v[152:153]
	v_pk_fma_f32 v[74:75], v[74:75], s[70:71], v[154:155]
	v_cvt_pk_bf16_f32 v244, v76, v77
	v_cvt_pk_bf16_f32 v245, v78, v79
	v_cvt_pk_bf16_f32 v246, v72, v73
	v_cvt_pk_bf16_f32 v247, v74, v75
	v_dot2c_f32_bf16_e32 v191, v244, v244
	v_dot2c_f32_bf16_e32 v191, v245, v245
	v_dot2c_f32_bf16_e32 v191, v246, v246
	v_dot2c_f32_bf16_e32 v191, v247, v247
	v_lshlrev_b32_e32 v148, 16, v248
	v_and_b32_e32 v149, 0xffff0000, v248
	v_lshlrev_b32_e32 v150, 16, v249
	v_and_b32_e32 v151, 0xffff0000, v249
	v_lshlrev_b32_e32 v152, 16, v250
	v_and_b32_e32 v153, 0xffff0000, v250
	v_lshlrev_b32_e32 v154, 16, v251
	v_and_b32_e32 v155, 0xffff0000, v251
	v_pk_fma_f32 v[68:69], v[68:69], s[70:71], v[148:149]
	v_pk_fma_f32 v[70:71], v[70:71], s[70:71], v[150:151]
	v_pk_fma_f32 v[64:65], v[64:65], s[70:71], v[152:153]
	v_pk_fma_f32 v[66:67], v[66:67], s[70:71], v[154:155]
	v_cvt_pk_bf16_f32 v248, v68, v69
	v_cvt_pk_bf16_f32 v249, v70, v71
	v_cvt_pk_bf16_f32 v250, v64, v65
	v_cvt_pk_bf16_f32 v251, v66, v67
	v_dot2c_f32_bf16_e32 v191, v248, v248
	v_dot2c_f32_bf16_e32 v191, v249, v249
	v_dot2c_f32_bf16_e32 v191, v250, v250
	v_dot2c_f32_bf16_e32 v191, v251, v251
	v_add_u32_e32 v180, 0x18000, v158
	global_store_dwordx4 v180, v[244:247], s[12:13]
	global_store_dwordx4 v180, v[248:251], s[12:13] offset:256
	v_mov_b32_e32 v148, v188
	v_mov_b32_e32 v150, v189
	v_mov_b32_e32 v152, v190
	v_mov_b32_e32 v154, v191
	s_nop 1
	v_permlane16_swap_b32_e32 v188, v148
	v_permlane16_swap_b32_e32 v189, v150
	v_permlane16_swap_b32_e32 v190, v152
	v_permlane16_swap_b32_e32 v191, v154
	v_add_f32_e32 v188, v188, v148
	v_add_f32_e32 v189, v189, v150
	v_add_f32_e32 v190, v190, v152
	v_add_f32_e32 v191, v191, v154
	v_mov_b32_e32 v148, v188
	v_mov_b32_e32 v150, v189
	v_mov_b32_e32 v152, v190
	v_mov_b32_e32 v154, v191
	s_nop 1
	v_permlane32_swap_b32_e32 v188, v148
	v_permlane32_swap_b32_e32 v189, v150
	v_permlane32_swap_b32_e32 v190, v152
	v_permlane32_swap_b32_e32 v191, v154
	v_add_f32_e32 v188, v188, v148
	v_add_f32_e32 v189, v189, v150
	v_add_f32_e32 v190, v190, v152
	v_add_f32_e32 v191, v191, v154
	v_mov_b32_e32 v181, v159
	s_and_saveexec_b64 s[86:87], s[6:7]
	s_cbranch_execz .Lresb_q0
	global_store_dword v181, v188, s[18:19]
	global_store_dword v181, v189, s[18:19] offset:1024
	global_store_dword v181, v190, s[18:19] offset:2048
	global_store_dword v181, v191, s[18:19] offset:3072
.Lresb_q0:
	s_or_b64 exec, exec, s[86:87]
	s_waitcnt vmcnt(18)
	v_lshlrev_b32_e32 v148, 16, v164
	v_and_b32_e32 v149, 0xffff0000, v164
	v_lshlrev_b32_e32 v150, 16, v165
	v_and_b32_e32 v151, 0xffff0000, v165
	v_lshlrev_b32_e32 v152, 16, v166
	v_and_b32_e32 v153, 0xffff0000, v166
	v_lshlrev_b32_e32 v154, 16, v167
	v_and_b32_e32 v155, 0xffff0000, v167
	v_pk_fma_f32 v[60:61], v[60:61], s[70:71], v[148:149]
	v_pk_fma_f32 v[62:63], v[62:63], s[70:71], v[150:151]
	v_pk_fma_f32 v[56:57], v[56:57], s[70:71], v[152:153]
	v_pk_fma_f32 v[58:59], v[58:59], s[70:71], v[154:155]
	v_cvt_pk_bf16_f32 v164, v60, v61
	v_cvt_pk_bf16_f32 v165, v62, v63
	v_cvt_pk_bf16_f32 v166, v56, v57
	v_cvt_pk_bf16_f32 v167, v58, v59
	v_dot2c_f32_bf16_e32 v192, v164, v164
	v_dot2c_f32_bf16_e32 v192, v165, v165
	v_dot2c_f32_bf16_e32 v192, v166, v166
	v_dot2c_f32_bf16_e32 v192, v167, v167
	v_lshlrev_b32_e32 v148, 16, v168
	v_and_b32_e32 v149, 0xffff0000, v168
	v_lshlrev_b32_e32 v150, 16, v169
	v_and_b32_e32 v151, 0xffff0000, v169
	v_lshlrev_b32_e32 v152, 16, v170
	v_and_b32_e32 v153, 0xffff0000, v170
	v_lshlrev_b32_e32 v154, 16, v171
	v_and_b32_e32 v155, 0xffff0000, v171
	v_pk_fma_f32 v[52:53], v[52:53], s[70:71], v[148:149]
	v_pk_fma_f32 v[54:55], v[54:55], s[70:71], v[150:151]
	v_pk_fma_f32 v[48:49], v[48:49], s[70:71], v[152:153]
	v_pk_fma_f32 v[50:51], v[50:51], s[70:71], v[154:155]
	v_cvt_pk_bf16_f32 v168, v52, v53
	v_cvt_pk_bf16_f32 v169, v54, v55
	v_cvt_pk_bf16_f32 v170, v48, v49
	v_cvt_pk_bf16_f32 v171, v50, v51
	v_dot2c_f32_bf16_e32 v192, v168, v168
	v_dot2c_f32_bf16_e32 v192, v169, v169
	v_dot2c_f32_bf16_e32 v192, v170, v170
	v_dot2c_f32_bf16_e32 v192, v171, v171
	v_add_u32_e32 v180, 0x40000, v158
	global_store_dwordx4 v180, v[164:167], s[12:13]
	global_store_dwordx4 v180, v[168:171], s[12:13] offset:256
	s_waitcnt vmcnt(18)
	v_lshlrev_b32_e32 v148, 16, v172
	v_and_b32_e32 v149, 0xffff0000, v172
	v_lshlrev_b32_e32 v150, 16, v173
	v_and_b32_e32 v151, 0xffff0000, v173
	v_lshlrev_b32_e32 v152, 16, v174
	v_and_b32_e32 v153, 0xffff0000, v174
	v_lshlrev_b32_e32 v154, 16, v175
	v_and_b32_e32 v155, 0xffff0000, v175
	v_pk_fma_f32 v[44:45], v[44:45], s[70:71], v[148:149]
	v_pk_fma_f32 v[46:47], v[46:47], s[70:71], v[150:151]
	v_pk_fma_f32 v[40:41], v[40:41], s[70:71], v[152:153]
	v_pk_fma_f32 v[42:43], v[42:43], s[70:71], v[154:155]
	v_cvt_pk_bf16_f32 v172, v44, v45
	v_cvt_pk_bf16_f32 v173, v46, v47
	v_cvt_pk_bf16_f32 v174, v40, v41
	v_cvt_pk_bf16_f32 v175, v42, v43
	v_dot2c_f32_bf16_e32 v193, v172, v172
	v_dot2c_f32_bf16_e32 v193, v173, v173
	v_dot2c_f32_bf16_e32 v193, v174, v174
	v_dot2c_f32_bf16_e32 v193, v175, v175
	v_lshlrev_b32_e32 v148, 16, v176
	v_and_b32_e32 v149, 0xffff0000, v176
	v_lshlrev_b32_e32 v150, 16, v177
	v_and_b32_e32 v151, 0xffff0000, v177
	v_lshlrev_b32_e32 v152, 16, v178
	v_and_b32_e32 v153, 0xffff0000, v178
	v_lshlrev_b32_e32 v154, 16, v179
	v_and_b32_e32 v155, 0xffff0000, v179
	v_pk_fma_f32 v[36:37], v[36:37], s[70:71], v[148:149]
	v_pk_fma_f32 v[38:39], v[38:39], s[70:71], v[150:151]
	v_pk_fma_f32 v[32:33], v[32:33], s[70:71], v[152:153]
	v_pk_fma_f32 v[34:35], v[34:35], s[70:71], v[154:155]
	v_cvt_pk_bf16_f32 v176, v36, v37
	v_cvt_pk_bf16_f32 v177, v38, v39
	v_cvt_pk_bf16_f32 v178, v32, v33
	v_cvt_pk_bf16_f32 v179, v34, v35
	v_dot2c_f32_bf16_e32 v193, v176, v176
	v_dot2c_f32_bf16_e32 v193, v177, v177
	v_dot2c_f32_bf16_e32 v193, v178, v178
	v_dot2c_f32_bf16_e32 v193, v179, v179
	v_add_u32_e32 v180, 0x48000, v158
	global_store_dwordx4 v180, v[172:175], s[12:13]
	global_store_dwordx4 v180, v[176:179], s[12:13] offset:256
	s_waitcnt vmcnt(16)
	v_lshlrev_b32_e32 v148, 16, v220
	v_and_b32_e32 v149, 0xffff0000, v220
	v_lshlrev_b32_e32 v150, 16, v221
	v_and_b32_e32 v151, 0xffff0000, v221
	v_lshlrev_b32_e32 v152, 16, v222
	v_and_b32_e32 v153, 0xffff0000, v222
	v_lshlrev_b32_e32 v154, 16, v223
	v_and_b32_e32 v155, 0xffff0000, v223
	v_pk_fma_f32 v[28:29], v[28:29], s[70:71], v[148:149]
	v_pk_fma_f32 v[30:31], v[30:31], s[70:71], v[150:151]
	v_pk_fma_f32 v[24:25], v[24:25], s[70:71], v[152:153]
	v_pk_fma_f32 v[26:27], v[26:27], s[70:71], v[154:155]
	v_cvt_pk_bf16_f32 v220, v28, v29
	v_cvt_pk_bf16_f32 v221, v30, v31
	v_cvt_pk_bf16_f32 v222, v24, v25
	v_cvt_pk_bf16_f32 v223, v26, v27
	v_dot2c_f32_bf16_e32 v252, v220, v220
	v_dot2c_f32_bf16_e32 v252, v221, v221
	v_dot2c_f32_bf16_e32 v252, v222, v222
	v_dot2c_f32_bf16_e32 v252, v223, v223
	v_lshlrev_b32_e32 v148, 16, v224
	v_and_b32_e32 v149, 0xffff0000, v224
	v_lshlrev_b32_e32 v150, 16, v225
	v_and_b32_e32 v151, 0xffff0000, v225
	v_lshlrev_b32_e32 v152, 16, v226
	v_and_b32_e32 v153, 0xffff0000, v226
	v_lshlrev_b32_e32 v154, 16, v227
	v_and_b32_e32 v155, 0xffff0000, v227
	v_pk_fma_f32 v[20:21], v[20:21], s[70:71], v[148:149]
	v_pk_fma_f32 v[22:23], v[22:23], s[70:71], v[150:151]
	v_pk_fma_f32 v[16:17], v[16:17], s[70:71], v[152:153]
	v_pk_fma_f32 v[18:19], v[18:19], s[70:71], v[154:155]
	v_cvt_pk_bf16_f32 v224, v20, v21
	v_cvt_pk_bf16_f32 v225, v22, v23
	v_cvt_pk_bf16_f32 v226, v16, v17
	v_cvt_pk_bf16_f32 v227, v18, v19
	v_dot2c_f32_bf16_e32 v252, v224, v224
	v_dot2c_f32_bf16_e32 v252, v225, v225
	v_dot2c_f32_bf16_e32 v252, v226, v226
	v_dot2c_f32_bf16_e32 v252, v227, v227
	v_add_u32_e32 v180, 0x50000, v158
	global_store_dwordx4 v180, v[220:223], s[12:13]
	global_store_dwordx4 v180, v[224:227], s[12:13] offset:256
	s_waitcnt vmcnt(14)
	v_lshlrev_b32_e32 v148, 16, v228
	v_and_b32_e32 v149, 0xffff0000, v228
	v_lshlrev_b32_e32 v150, 16, v229
	v_and_b32_e32 v151, 0xffff0000, v229
	v_lshlrev_b32_e32 v152, 16, v230
	v_and_b32_e32 v153, 0xffff0000, v230
	v_lshlrev_b32_e32 v154, 16, v231
	v_and_b32_e32 v155, 0xffff0000, v231
	v_pk_fma_f32 v[12:13], v[12:13], s[70:71], v[148:149]
	v_pk_fma_f32 v[14:15], v[14:15], s[70:71], v[150:151]
	v_pk_fma_f32 v[8:9], v[8:9], s[70:71], v[152:153]
	v_pk_fma_f32 v[10:11], v[10:11], s[70:71], v[154:155]
	v_cvt_pk_bf16_f32 v228, v12, v13
	v_cvt_pk_bf16_f32 v229, v14, v15
	v_cvt_pk_bf16_f32 v230, v8, v9
	v_cvt_pk_bf16_f32 v231, v10, v11
	v_dot2c_f32_bf16_e32 v253, v228, v228
	v_dot2c_f32_bf16_e32 v253, v229, v229
	v_dot2c_f32_bf16_e32 v253, v230, v230
	v_dot2c_f32_bf16_e32 v253, v231, v231
	v_lshlrev_b32_e32 v148, 16, v232
	v_and_b32_e32 v149, 0xffff0000, v232
	v_lshlrev_b32_e32 v150, 16, v233
	v_and_b32_e32 v151, 0xffff0000, v233
	v_lshlrev_b32_e32 v152, 16, v234
	v_and_b32_e32 v153, 0xffff0000, v234
	v_lshlrev_b32_e32 v154, 16, v235
	v_and_b32_e32 v155, 0xffff0000, v235
	v_pk_fma_f32 v[4:5], v[4:5], s[70:71], v[148:149]
	v_pk_fma_f32 v[6:7], v[6:7], s[70:71], v[150:151]
	v_pk_fma_f32 v[0:1], v[0:1], s[70:71], v[152:153]
	v_pk_fma_f32 v[2:3], v[2:3], s[70:71], v[154:155]
	v_cvt_pk_bf16_f32 v232, v4, v5
	v_cvt_pk_bf16_f32 v233, v6, v7
	v_cvt_pk_bf16_f32 v234, v0, v1
	v_cvt_pk_bf16_f32 v235, v2, v3
	v_dot2c_f32_bf16_e32 v253, v232, v232
	v_dot2c_f32_bf16_e32 v253, v233, v233
	v_dot2c_f32_bf16_e32 v253, v234, v234
	v_dot2c_f32_bf16_e32 v253, v235, v235
	v_add_u32_e32 v180, 0x58000, v158
	global_store_dwordx4 v180, v[228:231], s[12:13]
	global_store_dwordx4 v180, v[232:235], s[12:13] offset:256
	v_mov_b32_e32 v148, v192
	v_mov_b32_e32 v150, v193
	v_mov_b32_e32 v152, v252
	v_mov_b32_e32 v154, v253
	s_nop 1
	v_permlane16_swap_b32_e32 v192, v148
	v_permlane16_swap_b32_e32 v193, v150
	v_permlane16_swap_b32_e32 v252, v152
	v_permlane16_swap_b32_e32 v253, v154
	v_add_f32_e32 v192, v192, v148
	v_add_f32_e32 v193, v193, v150
	v_add_f32_e32 v252, v252, v152
	v_add_f32_e32 v253, v253, v154
	v_mov_b32_e32 v148, v192
	v_mov_b32_e32 v150, v193
	v_mov_b32_e32 v152, v252
	v_mov_b32_e32 v154, v253
	s_nop 1
	v_permlane32_swap_b32_e32 v192, v148
	v_permlane32_swap_b32_e32 v193, v150
	v_permlane32_swap_b32_e32 v252, v152
	v_permlane32_swap_b32_e32 v253, v154
	v_add_f32_e32 v192, v192, v148
	v_add_f32_e32 v193, v193, v150
	v_add_f32_e32 v252, v252, v152
	v_add_f32_e32 v253, v253, v154
	v_add_u32_e32 v181, 0x2000, v159
	s_and_saveexec_b64 s[86:87], s[6:7]
	s_cbranch_execz .Lresb_q1
	global_store_dword v181, v192, s[18:19]
	global_store_dword v181, v193, s[18:19] offset:1024
	global_store_dword v181, v252, s[18:19] offset:2048
	global_store_dword v181, v253, s[18:19] offset:3072
.Lresb_q1:
	s_or_b64 exec, exec, s[86:87]
.LBB0_329:
	s_or_b64 exec, exec, s[86:87]
	s_and_b64 vcc, exec, s[8:9]
	s_mov_b64 s[8:9], -1
	s_cbranch_vccnz .LBB0_297
	s_andn2_b64 vcc, exec, s[74:75]
	s_cbranch_vccnz .LBB0_296
	s_barrier
	s_branch .LBB0_296
